# GLU GEMM K-loop MFMAs also reordered into accumulate chains (dependency-respecting, symbolically verified), on top of the chain order in the other four loops
# baseline (speedup 1.0000x reference)
;     __device__ __forceinline__ void operator()(const f32x4 (&acc)[2][2][4][2], const Unit& u, int wr, int wc, int fr, int fq, int) const {
;     ...
;                 for (int bj = 0; bj < 2; ++bj) gl[m][bj] = *(const u32x4*)(YG + (size_t)(row0 + ai * HALF + m * 16) * 512 + col0 + bj * 32);
;             asm volatile("" ::: "memory");
; #pragma unroll
;             for (int m = 0; m < 4; ++m) { const int row = row0 + ai * HALF + m * 16;
; #pragma unroll
;                 for (int bj = 0; bj < 2; ++bj) { const int col = col0 + bj * 32; const u32x4 g = gl[m][bj];
;                     const f32x4 v0 = acc[ai][bj][m][0] + bb[bj][0], v1 = acc[ai][bj][m][1] + bb[bj][1];
;                     float o[8];
; #pragma unroll
; template <class Epi, class Sched, bool ALIGN_EPI = false, bool SP2 = false>
; __device__ __forceinline__ void gemm_phase(PG8_LAS unsigned char* lds, const Gemm g, const Sched& S, const Epi& E) {
;     ...
;         for (int t = 0; t < nt; t += 2) {
;             const bool last = (t == nt - 2);
;             const char* a1 = cA + (size_t)(t + 1) * kstep;
;             const char* a2 = last ? nA : cA + (size_t)(t + 2) * kstep; const char* b2 = last ? nB : cB + (size_t)(t + 2) * kstep;
;             const char* a3 = a2 + kstep; const char* b3 = b2 + kstep;
;             if (last && has_next) S.a_ready(nxt);
;             if constexpr (SP2) {
;             PG8_LDB(B0, 0, 0); PG8_LDB(B1, 0, 1); PG8_SCHED; PG8_LDA(At, 0, 0); PG8_STAGE(PG8_SA(1, 1), a1 + hstep, voffA);
;             PG8_WAIT_V(8); PG8_WAIT_L(0); PG8_BAR; PG8_MMA(0, 0, At, B0); PG8_MMA(0, 1, At, B1); PG8_BAR; PG8_SCHED;
;             PG8_LDA(At, 0, 1); PG8_STAGE(PG8_SB(0, 0), b2, voffB); PG8_STAGE(PG8_SB(0, 1), b2 + hstepB, voffB); PG8_STAGE(PG8_SA(0, 0), a2, voffA);
;             PG8_WAIT_V(8); PG8_WAIT_L(0); PG8_BAR; PG8_MMA(1, 0, At, B0); PG8_MMA(1, 1, At, B1); PG8_BAR; PG8_SCHED;
;             PG8_LDB(B0, 1, 0); PG8_LDB(B1, 1, 1); PG8_SCHED; PG8_LDA(At, 1, 0); PG8_STAGE(PG8_SA(0, 1), a2 + hstep, voffA);
;             PG8_WAIT_V(8); PG8_WAIT_L(0); PG8_BAR; PG8_MMA(0, 0, At, B0); PG8_MMA(0, 1, At, B1); PG8_BAR; PG8_SCHED;
;             PG8_LDA(At, 1, 1); PG8_STAGE(PG8_SB(1, 0), b3, voffB); PG8_STAGE(PG8_SB(1, 1), b3 + hstepB, voffB); PG8_STAGE(PG8_SA(1, 0), a3, voffA);
;             PG8_WAIT_V(8); PG8_WAIT_L(0); PG8_BAR; PG8_MMA(1, 0, At, B0); PG8_MMA(1, 1, At, B1); PG8_BAR; PG8_SCHED;
.LBB0_788:
	s_add_u32 s9, s68, 0xfffe0080
	s_addc_u32 s10, s69, -1
	s_add_i32 s11, 0, 0x10000
	s_cmp_eq_u32 s8, 4
	s_cselect_b32 s77, s36, s10
	s_cselect_b32 s76, s37, s9
	s_cselect_b32 s73, s4, s7
	s_cselect_b32 s72, s5, s6
	s_add_i32 s9, 0, 0x14000
	ds_read_b128 v[34:37], v186
	ds_read_b128 v[38:41], v186 offset:1024
	ds_read_b128 v[50:53], v186 offset:2048
	ds_read_b128 v[54:57], v186 offset:3072
	ds_read_b128 v[114:117], v187
	ds_read_b128 v[126:129], v187 offset:1024
	ds_read_b128 v[138:141], v187 offset:2048
	ds_read_b128 v[150:153], v187 offset:3072
	s_add_i32 m0, s66, 0xc000
	ds_read_b128 v[154:157], v217
	ds_read_b128 v[158:161], v217 offset:1024
	ds_read_b128 v[170:173], v217 offset:2048
	ds_read_b128 v[206:209], v217 offset:3072
	ds_read_b128 v[210:213], v217 offset:4096
	ds_read_b128 v[218:221], v217 offset:5120
	ds_read_b128 v[236:239], v217 offset:6144
	ds_read_b128 v[240:243], v217 offset:7168
	global_load_lds_dwordx4 v180, s[68:69]
	s_add_i32 m0, s66, 0xe000
	s_nop 0
	global_load_lds_dwordx4 v182, s[68:69]
	s_waitcnt vmcnt(8)
	s_waitcnt lgkmcnt(0)
	s_barrier
	v_mfma_f32_16x16x32_bf16 v[166:169], v[34:37], v[154:157], v[166:169]
	v_mfma_f32_16x16x32_bf16 v[166:169], v[38:41], v[158:161], v[166:169]
	v_mfma_f32_16x16x32_bf16 v[162:165], v[50:53], v[154:157], v[162:165]
	v_mfma_f32_16x16x32_bf16 v[162:165], v[54:57], v[158:161], v[162:165]
	v_mfma_f32_16x16x32_bf16 v[134:137], v[34:37], v[170:173], v[134:137]
	v_mfma_f32_16x16x32_bf16 v[134:137], v[38:41], v[206:209], v[134:137]
	v_mfma_f32_16x16x32_bf16 v[130:133], v[50:53], v[170:173], v[130:133]
	v_mfma_f32_16x16x32_bf16 v[130:133], v[54:57], v[206:209], v[130:133]
	v_mfma_f32_16x16x32_bf16 v[110:113], v[34:37], v[210:213], v[110:113]
	v_mfma_f32_16x16x32_bf16 v[110:113], v[38:41], v[218:221], v[110:113]
	v_mfma_f32_16x16x32_bf16 v[106:109], v[50:53], v[210:213], v[106:109]
	v_mfma_f32_16x16x32_bf16 v[106:109], v[54:57], v[218:221], v[106:109]
	v_mfma_f32_16x16x32_bf16 v[94:97], v[34:37], v[236:239], v[94:97]
	v_mfma_f32_16x16x32_bf16 v[94:97], v[38:41], v[240:243], v[94:97]
	v_mfma_f32_16x16x32_bf16 v[90:93], v[50:53], v[236:239], v[90:93]
	v_mfma_f32_16x16x32_bf16 v[90:93], v[54:57], v[240:243], v[90:93]
	v_mfma_f32_16x16x32_bf16 v[146:149], v[114:117], v[154:157], v[146:149]
	v_mfma_f32_16x16x32_bf16 v[146:149], v[126:129], v[158:161], v[146:149]
	v_mfma_f32_16x16x32_bf16 v[142:145], v[138:141], v[154:157], v[142:145]
	v_mfma_f32_16x16x32_bf16 v[142:145], v[150:153], v[158:161], v[142:145]
	v_mfma_f32_16x16x32_bf16 v[122:125], v[114:117], v[170:173], v[122:125]
	v_mfma_f32_16x16x32_bf16 v[122:125], v[126:129], v[206:209], v[122:125]
	v_mfma_f32_16x16x32_bf16 v[118:121], v[138:141], v[170:173], v[118:121]
	v_mfma_f32_16x16x32_bf16 v[118:121], v[150:153], v[206:209], v[118:121]
	v_mfma_f32_16x16x32_bf16 v[102:105], v[114:117], v[210:213], v[102:105]
	v_mfma_f32_16x16x32_bf16 v[102:105], v[126:129], v[218:221], v[102:105]
	v_mfma_f32_16x16x32_bf16 v[98:101], v[138:141], v[210:213], v[98:101]
	v_mfma_f32_16x16x32_bf16 v[98:101], v[150:153], v[218:221], v[98:101]
	v_mfma_f32_16x16x32_bf16 v[86:89], v[114:117], v[236:239], v[86:89]
	v_mfma_f32_16x16x32_bf16 v[86:89], v[126:129], v[240:243], v[86:89]
	v_mfma_f32_16x16x32_bf16 v[82:85], v[138:141], v[236:239], v[82:85]
	v_mfma_f32_16x16x32_bf16 v[82:85], v[150:153], v[240:243], v[82:85]
	s_barrier
	s_add_i32 s10, s11, s25
	s_mov_b32 m0, s10
	ds_read_b128 v[154:157], v217 offset:16384
	ds_read_b128 v[158:161], v217 offset:17408
	ds_read_b128 v[170:173], v217 offset:18432
	ds_read_b128 v[206:209], v217 offset:19456
	ds_read_b128 v[210:213], v217 offset:20480
	ds_read_b128 v[218:221], v217 offset:21504
	ds_read_b128 v[236:239], v217 offset:22528
	ds_read_b128 v[240:243], v217 offset:23552
	global_load_lds_dwordx4 v190, s[72:73]
	s_add_i32 m0, s10, 0x2000
	s_add_u32 s10, s72, 0x8000
	s_addc_u32 s11, s73, 0
	s_add_i32 s9, s9, s25
	global_load_lds_dwordx4 v174, s[72:73]
	s_mov_b32 m0, s9
	s_nop 0
	global_load_lds_dwordx4 v190, s[10:11]
	s_add_i32 m0, s9, 0x2000
	s_nop 0
	global_load_lds_dwordx4 v174, s[10:11]
	s_mov_b32 m0, s66
	s_nop 0
	global_load_lds_dwordx4 v178, s[76:77]
	s_mov_b32 m0, s67
	s_nop 0
	global_load_lds_dwordx4 v176, s[76:77]
	s_waitcnt vmcnt(8)
	s_waitcnt lgkmcnt(0)
	s_barrier
	v_mfma_f32_16x16x32_bf16 v[78:81], v[34:37], v[154:157], v[78:81]
	v_mfma_f32_16x16x32_bf16 v[78:81], v[38:41], v[158:161], v[78:81]
	v_mfma_f32_16x16x32_bf16 v[74:77], v[50:53], v[154:157], v[74:77]
	v_mfma_f32_16x16x32_bf16 v[74:77], v[54:57], v[158:161], v[74:77]
	v_mfma_f32_16x16x32_bf16 v[62:65], v[34:37], v[170:173], v[62:65]
	v_mfma_f32_16x16x32_bf16 v[62:65], v[38:41], v[206:209], v[62:65]
	v_mfma_f32_16x16x32_bf16 v[58:61], v[50:53], v[170:173], v[58:61]
	v_mfma_f32_16x16x32_bf16 v[58:61], v[54:57], v[206:209], v[58:61]
	v_mfma_f32_16x16x32_bf16 v[30:33], v[34:37], v[210:213], v[30:33]
	v_mfma_f32_16x16x32_bf16 v[30:33], v[38:41], v[218:221], v[30:33]
	v_mfma_f32_16x16x32_bf16 v[26:29], v[50:53], v[210:213], v[26:29]
	v_mfma_f32_16x16x32_bf16 v[26:29], v[54:57], v[218:221], v[26:29]
	v_mfma_f32_16x16x32_bf16 v[14:17], v[34:37], v[236:239], v[14:17]
	v_mfma_f32_16x16x32_bf16 v[14:17], v[38:41], v[240:243], v[14:17]
	v_mfma_f32_16x16x32_bf16 v[10:13], v[50:53], v[236:239], v[10:13]
	v_mfma_f32_16x16x32_bf16 v[10:13], v[54:57], v[240:243], v[10:13]
	v_mfma_f32_16x16x32_bf16 v[46:49], v[114:117], v[170:173], v[46:49]
	v_mfma_f32_16x16x32_bf16 v[46:49], v[126:129], v[206:209], v[46:49]
	v_mfma_f32_16x16x32_bf16 v[42:45], v[138:141], v[170:173], v[42:45]
	v_mfma_f32_16x16x32_bf16 v[42:45], v[150:153], v[206:209], v[42:45]
	v_mfma_f32_16x16x32_bf16 v[22:25], v[114:117], v[210:213], v[22:25]
	v_mfma_f32_16x16x32_bf16 v[22:25], v[126:129], v[218:221], v[22:25]
	v_mfma_f32_16x16x32_bf16 v[18:21], v[138:141], v[210:213], v[18:21]
	v_mfma_f32_16x16x32_bf16 v[18:21], v[150:153], v[218:221], v[18:21]
	v_mfma_f32_16x16x32_bf16 v[6:9], v[114:117], v[236:239], v[6:9]
	v_mfma_f32_16x16x32_bf16 v[6:9], v[126:129], v[240:243], v[6:9]
	v_mfma_f32_16x16x32_bf16 v[2:5], v[138:141], v[236:239], v[2:5]
	v_mfma_f32_16x16x32_bf16 v[2:5], v[150:153], v[240:243], v[2:5]
	v_mfma_f32_16x16x32_bf16 v[34:37], v[114:117], v[154:157], v[70:73]
	v_mfma_f32_16x16x32_bf16 v[34:37], v[126:129], v[158:161], v[34:37]
	v_mfma_f32_16x16x32_bf16 v[38:41], v[138:141], v[154:157], v[66:69]
	v_mfma_f32_16x16x32_bf16 v[38:41], v[150:153], v[158:161], v[38:41]
	s_barrier
;     __device__ __forceinline__ void operator()(const f32x4 (&acc)[2][2][4][2], const Unit& u, int wr, int wc, int fr, int fq, int) const {
;     ...
;                 for (int bj = 0; bj < 2; ++bj) gl[m][bj] = *(const u32x4*)(YG + (size_t)(row0 + ai * HALF + m * 16) * 512 + col0 + bj * 32);
;             asm volatile("" ::: "memory");
; #pragma unroll
;             for (int m = 0; m < 4; ++m) { const int row = row0 + ai * HALF + m * 16;
; #pragma unroll
;                 for (int bj = 0; bj < 2; ++bj) { const int col = col0 + bj * 32; const u32x4 g = gl[m][bj];
;                     const f32x4 v0 = acc[ai][bj][m][0] + bb[bj][0], v1 = acc[ai][bj][m][1] + bb[bj][1];
;                     float o[8];
; #pragma unroll
; template <class Epi, class Sched, bool ALIGN_EPI = false, bool SP2 = false>
; __device__ __forceinline__ void gemm_phase(PG8_LAS unsigned char* lds, const Gemm g, const Sched& S, const Epi& E) {
;     ...
;         for (int t = 0; t < nt; t += 2) {
;             const bool last = (t == nt - 2);
;             const char* a1 = cA + (size_t)(t + 1) * kstep;
;             const char* a2 = last ? nA : cA + (size_t)(t + 2) * kstep; const char* b2 = last ? nB : cB + (size_t)(t + 2) * kstep;
;             const char* a3 = a2 + kstep; const char* b3 = b2 + kstep;
;             if (last && has_next) S.a_ready(nxt);
;             if constexpr (SP2) {
;             PG8_LDB(B0, 0, 0); PG8_LDB(B1, 0, 1); PG8_SCHED; PG8_LDA(At, 0, 0); PG8_STAGE(PG8_SA(1, 1), a1 + hstep, voffA);
;             PG8_WAIT_V(8); PG8_WAIT_L(0); PG8_BAR; PG8_MMA(0, 0, At, B0); PG8_MMA(0, 1, At, B1); PG8_BAR; PG8_SCHED;
;             PG8_LDA(At, 0, 1); PG8_STAGE(PG8_SB(0, 0), b2, voffB); PG8_STAGE(PG8_SB(0, 1), b2 + hstepB, voffB); PG8_STAGE(PG8_SA(0, 0), a2, voffA);
;             PG8_WAIT_V(8); PG8_WAIT_L(0); PG8_BAR; PG8_MMA(1, 0, At, B0); PG8_MMA(1, 1, At, B1); PG8_BAR; PG8_SCHED;
;             PG8_LDB(B0, 1, 0); PG8_LDB(B1, 1, 1); PG8_SCHED; PG8_LDA(At, 1, 0); PG8_STAGE(PG8_SA(0, 1), a2 + hstep, voffA);
;             PG8_WAIT_V(8); PG8_WAIT_L(0); PG8_BAR; PG8_MMA(0, 0, At, B0); PG8_MMA(0, 1, At, B1); PG8_BAR; PG8_SCHED;
;             PG8_LDA(At, 1, 1); PG8_STAGE(PG8_SB(1, 0), b3, voffB); PG8_STAGE(PG8_SB(1, 1), b3 + hstepB, voffB); PG8_STAGE(PG8_SA(1, 0), a3, voffA);
;             PG8_WAIT_V(8); PG8_WAIT_L(0); PG8_BAR; PG8_MMA(1, 0, At, B0); PG8_MMA(1, 1, At, B1); PG8_BAR; PG8_SCHED;
	s_add_i32 s9, 0, 0x18000
	s_add_i32 s12, 0, 0x1c000
	ds_read_b128 v[50:53], v198
	ds_read_b128 v[54:57], v198 offset:1024
	ds_read_b128 v[66:69], v198 offset:2048
	ds_read_b128 v[70:73], v198 offset:3072
	ds_read_b128 v[114:117], v199
	ds_read_b128 v[126:129], v199 offset:1024
	ds_read_b128 v[138:141], v199 offset:2048
	ds_read_b128 v[150:153], v199 offset:3072
	s_add_u32 s10, s76, 0x20000
	s_addc_u32 s11, s77, 0
	s_mov_b32 m0, s80
	ds_read_b128 v[154:157], v217 offset:32768
	ds_read_b128 v[158:161], v217 offset:33792
	ds_read_b128 v[170:173], v217 offset:34816
	ds_read_b128 v[206:209], v217 offset:35840
	ds_read_b128 v[210:213], v217 offset:36864
	ds_read_b128 v[218:221], v217 offset:37888
	ds_read_b128 v[236:239], v217 offset:38912
	ds_read_b128 v[240:243], v217 offset:39936
	global_load_lds_dwordx4 v178, s[10:11]
	s_mov_b32 m0, s81
	s_nop 0
	global_load_lds_dwordx4 v176, s[10:11]
	s_waitcnt vmcnt(8)
	s_waitcnt lgkmcnt(0)
	s_barrier
	v_mfma_f32_16x16x32_bf16 v[166:169], v[50:53], v[154:157], v[166:169]
	v_mfma_f32_16x16x32_bf16 v[166:169], v[54:57], v[158:161], v[166:169]
	v_mfma_f32_16x16x32_bf16 v[162:165], v[66:69], v[154:157], v[162:165]
	v_mfma_f32_16x16x32_bf16 v[162:165], v[70:73], v[158:161], v[162:165]
	v_mfma_f32_16x16x32_bf16 v[134:137], v[50:53], v[170:173], v[134:137]
	v_mfma_f32_16x16x32_bf16 v[134:137], v[54:57], v[206:209], v[134:137]
	v_mfma_f32_16x16x32_bf16 v[130:133], v[66:69], v[170:173], v[130:133]
	v_mfma_f32_16x16x32_bf16 v[130:133], v[70:73], v[206:209], v[130:133]
	v_mfma_f32_16x16x32_bf16 v[110:113], v[50:53], v[210:213], v[110:113]
	v_mfma_f32_16x16x32_bf16 v[110:113], v[54:57], v[218:221], v[110:113]
	v_mfma_f32_16x16x32_bf16 v[106:109], v[66:69], v[210:213], v[106:109]
	v_mfma_f32_16x16x32_bf16 v[106:109], v[70:73], v[218:221], v[106:109]
	v_mfma_f32_16x16x32_bf16 v[94:97], v[50:53], v[236:239], v[94:97]
	v_mfma_f32_16x16x32_bf16 v[94:97], v[54:57], v[240:243], v[94:97]
	v_mfma_f32_16x16x32_bf16 v[90:93], v[66:69], v[236:239], v[90:93]
	v_mfma_f32_16x16x32_bf16 v[90:93], v[70:73], v[240:243], v[90:93]
	v_mfma_f32_16x16x32_bf16 v[146:149], v[114:117], v[154:157], v[146:149]
	v_mfma_f32_16x16x32_bf16 v[146:149], v[126:129], v[158:161], v[146:149]
	v_mfma_f32_16x16x32_bf16 v[142:145], v[138:141], v[154:157], v[142:145]
	v_mfma_f32_16x16x32_bf16 v[142:145], v[150:153], v[158:161], v[142:145]
	v_mfma_f32_16x16x32_bf16 v[122:125], v[114:117], v[170:173], v[122:125]
	v_mfma_f32_16x16x32_bf16 v[122:125], v[126:129], v[206:209], v[122:125]
	v_mfma_f32_16x16x32_bf16 v[118:121], v[138:141], v[170:173], v[118:121]
	v_mfma_f32_16x16x32_bf16 v[118:121], v[150:153], v[206:209], v[118:121]
	v_mfma_f32_16x16x32_bf16 v[102:105], v[114:117], v[210:213], v[102:105]
	v_mfma_f32_16x16x32_bf16 v[102:105], v[126:129], v[218:221], v[102:105]
	v_mfma_f32_16x16x32_bf16 v[98:101], v[138:141], v[210:213], v[98:101]
	v_mfma_f32_16x16x32_bf16 v[98:101], v[150:153], v[218:221], v[98:101]
	v_mfma_f32_16x16x32_bf16 v[86:89], v[114:117], v[236:239], v[86:89]
	v_mfma_f32_16x16x32_bf16 v[86:89], v[126:129], v[240:243], v[86:89]
	v_mfma_f32_16x16x32_bf16 v[82:85], v[138:141], v[236:239], v[82:85]
	v_mfma_f32_16x16x32_bf16 v[82:85], v[150:153], v[240:243], v[82:85]
	s_barrier
	s_add_i32 s9, s9, s25
	s_mov_b32 m0, s9
	ds_read_b128 v[154:157], v217 offset:49152
	ds_read_b128 v[158:161], v217 offset:50176
	ds_read_b128 v[170:173], v217 offset:51200
	ds_read_b128 v[206:209], v217 offset:52224
	ds_read_b128 v[210:213], v217 offset:53248
	ds_read_b128 v[218:221], v217 offset:54272
	ds_read_b128 v[236:239], v217 offset:55296
	ds_read_b128 v[240:243], v217 offset:56320
	s_add_u32 s100, s72, s60
	s_addc_u32 s101, s73, s61
	global_load_lds_dwordx4 v190, s[100:101]
	s_add_i32 m0, s9, 0x2000
	s_add_u32 s10, s72, 0x8080
	s_addc_u32 s11, s73, 0
	s_add_i32 s9, s12, s25
	global_load_lds_dwordx4 v174, s[100:101]
	s_mov_b32 m0, s9
	s_nop 0
	global_load_lds_dwordx4 v190, s[10:11]
	s_add_i32 m0, s9, 0x2000
	s_nop 0
	global_load_lds_dwordx4 v174, s[10:11]
	s_mov_b32 m0, s82
	s_add_u32 s100, s76, s60
	s_addc_u32 s101, s77, s61
	global_load_lds_dwordx4 v178, s[100:101]
	s_mov_b32 m0, s92
	s_nop 0
	global_load_lds_dwordx4 v176, s[100:101]
	s_waitcnt vmcnt(8)
	s_waitcnt lgkmcnt(0)
	s_barrier
	v_mfma_f32_16x16x32_bf16 v[78:81], v[50:53], v[154:157], v[78:81]
	v_mfma_f32_16x16x32_bf16 v[78:81], v[54:57], v[158:161], v[78:81]
	v_mfma_f32_16x16x32_bf16 v[74:77], v[66:69], v[154:157], v[74:77]
	v_mfma_f32_16x16x32_bf16 v[74:77], v[70:73], v[158:161], v[74:77]
	v_mfma_f32_16x16x32_bf16 v[62:65], v[50:53], v[170:173], v[62:65]
	v_mfma_f32_16x16x32_bf16 v[62:65], v[54:57], v[206:209], v[62:65]
	v_mfma_f32_16x16x32_bf16 v[58:61], v[66:69], v[170:173], v[58:61]
	v_mfma_f32_16x16x32_bf16 v[58:61], v[70:73], v[206:209], v[58:61]
	v_mfma_f32_16x16x32_bf16 v[30:33], v[50:53], v[210:213], v[30:33]
	v_mfma_f32_16x16x32_bf16 v[30:33], v[54:57], v[218:221], v[30:33]
	v_mfma_f32_16x16x32_bf16 v[26:29], v[66:69], v[210:213], v[26:29]
	v_mfma_f32_16x16x32_bf16 v[26:29], v[70:73], v[218:221], v[26:29]
	v_mfma_f32_16x16x32_bf16 v[14:17], v[50:53], v[236:239], v[14:17]
	v_mfma_f32_16x16x32_bf16 v[14:17], v[54:57], v[240:243], v[14:17]
	v_mfma_f32_16x16x32_bf16 v[10:13], v[66:69], v[236:239], v[10:13]
	v_mfma_f32_16x16x32_bf16 v[10:13], v[70:73], v[240:243], v[10:13]
	v_mfma_f32_16x16x32_bf16 v[34:37], v[114:117], v[154:157], v[34:37]
	v_mfma_f32_16x16x32_bf16 v[70:73], v[126:129], v[158:161], v[34:37]
	v_mfma_f32_16x16x32_bf16 v[34:37], v[138:141], v[154:157], v[38:41]
	v_mfma_f32_16x16x32_bf16 v[66:69], v[150:153], v[158:161], v[34:37]
	v_mfma_f32_16x16x32_bf16 v[34:37], v[114:117], v[170:173], v[46:49]
	v_mfma_f32_16x16x32_bf16 v[46:49], v[126:129], v[206:209], v[34:37]
	v_mfma_f32_16x16x32_bf16 v[34:37], v[138:141], v[170:173], v[42:45]
	v_mfma_f32_16x16x32_bf16 v[42:45], v[150:153], v[206:209], v[34:37]
	v_mfma_f32_16x16x32_bf16 v[22:25], v[114:117], v[210:213], v[22:25]
	v_mfma_f32_16x16x32_bf16 v[22:25], v[126:129], v[218:221], v[22:25]
	v_mfma_f32_16x16x32_bf16 v[18:21], v[138:141], v[210:213], v[18:21]
	v_mfma_f32_16x16x32_bf16 v[18:21], v[150:153], v[218:221], v[18:21]
	v_mfma_f32_16x16x32_bf16 v[6:9], v[114:117], v[236:239], v[6:9]
	v_mfma_f32_16x16x32_bf16 v[6:9], v[126:129], v[240:243], v[6:9]
	v_mfma_f32_16x16x32_bf16 v[2:5], v[138:141], v[236:239], v[2:5]
	v_mfma_f32_16x16x32_bf16 v[2:5], v[150:153], v[240:243], v[2:5]
	s_barrier
	s_add_i32 s8, s8, 2
	s_add_u32 s68, s68, 0x100
	s_addc_u32 s69, s69, 0
	s_add_u32 s6, s6, 0x100
	s_addc_u32 s7, s7, 0
	s_cmp_gt_u32 s8, 5
	s_cbranch_scc0 .LBB0_788
	s_and_b64 vcc, exec, s[46:47]
	s_cbranch_vccz .LBB0_791
	s_barrier
